# grid barrier: non-leader workgroups poll the top-level generation word directly instead of the per-XCD generation (one hop less)
# baseline (speedup 1.0000x reference)
.LBB0_290:
	s_or_b64 exec, exec, s[8:9]
	v_cvt_f32_u32_e32 v4, v2
	s_waitcnt vmcnt(0)
	v_readfirstlane_b32 s8, v3
	v_sub_u32_e32 v3, 0, v2
	v_rcp_iflag_f32_e32 v4, v4
	v_add_u32_e32 v5, s8, v1
	v_mul_f32_e32 v4, 0x4f7ffffe, v4
	v_cvt_u32_f32_e32 v4, v4
	v_mul_lo_u32 v1, v3, v4
	v_mul_hi_u32 v1, v4, v1
	v_add_u32_e32 v1, v4, v1
	v_mul_hi_u32 v1, v5, v1
	v_mul_lo_u32 v3, v1, v2
	v_sub_u32_e32 v3, v5, v3
	v_add_u32_e32 v4, 1, v1
	v_cmp_ge_u32_e32 vcc, v3, v2
	s_nop 1
	v_cndmask_b32_e32 v1, v1, v4, vcc
	v_sub_u32_e32 v4, v3, v2
	v_cndmask_b32_e32 v3, v3, v4, vcc
	v_add_u32_e32 v4, 1, v1
	v_cmp_ge_u32_e32 vcc, v3, v2
	v_add_u32_e32 v3, 1, v5
	s_nop 0
	v_cndmask_b32_e32 v1, v1, v4, vcc
	v_mul_lo_u32 v4, v2, v1
	v_add_u32_e32 v2, v4, v2
	v_cmp_ne_u32_e32 vcc, v3, v2
	s_and_saveexec_b64 s[8:9], vcc
	s_xor_b64 s[8:9], exec, s[8:9]
	s_cbranch_execz .LBB0_304
	v_readlane_b32 s10, v253, 9
	v_readlane_b32 s11, v253, 10
	s_waitcnt lgkmcnt(0)
	s_nop 3
	global_load_dword v0, v113, s[10:11] sc1
	s_waitcnt vmcnt(0)
	v_cmp_eq_u32_e32 vcc, v0, v1
	s_and_saveexec_b64 s[10:11], vcc
	s_cbranch_execz .LBB0_303
	s_mov_b32 s34, 1
	s_mov_b64 s[12:13], 0
	s_branch .LBB0_294

.LBB0_296:
	v_readlane_b32 s16, v253, 9
	v_readlane_b32 s17, v253, 10
	s_add_i32 s34, s34, 1
	s_mov_b64 s[18:19], -1
	s_nop 2
	global_load_dword v0, v113, s[16:17] sc1
	s_waitcnt vmcnt(0)
	v_cmp_ne_u32_e32 vcc, v0, v1
	s_orn2_b64 s[16:17], vcc, exec
	s_branch .LBB0_293

.LBB0_352:
	s_or_b64 exec, exec, s[6:7]
	v_cvt_f32_u32_e32 v4, v2
	s_waitcnt vmcnt(0)
	v_readfirstlane_b32 s6, v3
	v_sub_u32_e32 v3, 0, v2
	v_rcp_iflag_f32_e32 v4, v4
	v_add_u32_e32 v5, s6, v1
	v_mul_f32_e32 v4, 0x4f7ffffe, v4
	v_cvt_u32_f32_e32 v4, v4
	v_mul_lo_u32 v1, v3, v4
	v_mul_hi_u32 v1, v4, v1
	v_add_u32_e32 v1, v4, v1
	v_mul_hi_u32 v1, v5, v1
	v_mul_lo_u32 v3, v1, v2
	v_sub_u32_e32 v3, v5, v3
	v_add_u32_e32 v4, 1, v1
	v_cmp_ge_u32_e32 vcc, v3, v2
	s_nop 1
	v_cndmask_b32_e32 v1, v1, v4, vcc
	v_sub_u32_e32 v4, v3, v2
	v_cndmask_b32_e32 v3, v3, v4, vcc
	v_add_u32_e32 v4, 1, v1
	v_cmp_ge_u32_e32 vcc, v3, v2
	v_add_u32_e32 v3, 1, v5
	s_nop 0
	v_cndmask_b32_e32 v1, v1, v4, vcc
	v_mul_lo_u32 v4, v2, v1
	v_add_u32_e32 v2, v4, v2
	v_cmp_ne_u32_e32 vcc, v3, v2
	s_and_saveexec_b64 s[6:7], vcc
	s_xor_b64 s[6:7], exec, s[6:7]
	s_cbranch_execz .LBB0_366
	v_readlane_b32 s8, v253, 9
	v_readlane_b32 s9, v253, 10
	s_waitcnt lgkmcnt(0)
	s_nop 3
	global_load_dword v0, v113, s[8:9] sc1
	s_waitcnt vmcnt(0)
	v_cmp_eq_u32_e32 vcc, v0, v1
	s_and_saveexec_b64 s[8:9], vcc
	s_cbranch_execz .LBB0_365
	s_mov_b32 s30, 1
	s_mov_b64 s[10:11], 0
	s_branch .LBB0_356

.LBB0_358:
	v_readlane_b32 s14, v253, 9
	v_readlane_b32 s15, v253, 10
	s_add_i32 s30, s30, 1
	s_mov_b64 s[16:17], -1
	s_nop 2
	global_load_dword v0, v113, s[14:15] sc1
	s_waitcnt vmcnt(0)
	v_cmp_ne_u32_e32 vcc, v0, v1
	s_orn2_b64 s[14:15], vcc, exec
	s_branch .LBB0_355

.LBB0_664:
	s_or_b64 exec, exec, s[6:7]
	v_cvt_f32_u32_e32 v4, v2
	s_waitcnt vmcnt(0)
	v_readfirstlane_b32 s6, v3
	v_sub_u32_e32 v3, 0, v2
	v_rcp_iflag_f32_e32 v4, v4
	v_add_u32_e32 v5, s6, v1
	v_mul_f32_e32 v4, 0x4f7ffffe, v4
	v_cvt_u32_f32_e32 v4, v4
	v_mul_lo_u32 v1, v3, v4
	v_mul_hi_u32 v1, v4, v1
	v_add_u32_e32 v1, v4, v1
	v_mul_hi_u32 v1, v5, v1
	v_mul_lo_u32 v3, v1, v2
	v_sub_u32_e32 v3, v5, v3
	v_add_u32_e32 v4, 1, v1
	v_cmp_ge_u32_e32 vcc, v3, v2
	s_nop 1
	v_cndmask_b32_e32 v1, v1, v4, vcc
	v_sub_u32_e32 v4, v3, v2
	v_cndmask_b32_e32 v3, v3, v4, vcc
	v_add_u32_e32 v4, 1, v1
	v_cmp_ge_u32_e32 vcc, v3, v2
	v_add_u32_e32 v3, 1, v5
	s_nop 0
	v_cndmask_b32_e32 v1, v1, v4, vcc
	v_mul_lo_u32 v4, v2, v1
	v_add_u32_e32 v2, v4, v2
	v_cmp_ne_u32_e32 vcc, v3, v2
	s_and_saveexec_b64 s[6:7], vcc
	s_xor_b64 s[6:7], exec, s[6:7]
	s_cbranch_execz .LBB0_678
	v_readlane_b32 s8, v253, 9
	v_readlane_b32 s9, v253, 10
	s_waitcnt lgkmcnt(0)
	s_nop 3
	global_load_dword v0, v113, s[8:9] sc1
	s_waitcnt vmcnt(0)
	v_cmp_eq_u32_e32 vcc, v0, v1
	s_and_saveexec_b64 s[8:9], vcc
	s_cbranch_execz .LBB0_677
	s_mov_b32 s34, 1
	s_mov_b64 s[10:11], 0
	s_branch .LBB0_668

.LBB0_670:
	v_readlane_b32 s14, v253, 9
	v_readlane_b32 s15, v253, 10
	s_add_i32 s34, s34, 1
	s_mov_b64 s[16:17], -1
	s_nop 2
	global_load_dword v0, v113, s[14:15] sc1
	s_waitcnt vmcnt(0)
	v_cmp_ne_u32_e32 vcc, v0, v1
	s_orn2_b64 s[14:15], vcc, exec
	s_branch .LBB0_667

.LBB0_970:
	v_readlane_b32 s14, v253, 9
	v_readlane_b32 s15, v253, 10
	s_add_i32 s34, s34, 1
	s_mov_b64 s[18:19], -1
	s_nop 2
	global_load_dword v0, v113, s[14:15] sc1
	s_waitcnt vmcnt(0)
	v_cmp_ne_u32_e32 vcc, v0, v1
	s_orn2_b64 s[14:15], vcc, exec
	s_branch .LBB0_967

.LBB0_1642:
	s_or_b64 exec, exec, s[10:11]
	v_cvt_f32_u32_e32 v4, v2
	s_waitcnt vmcnt(0)
	v_readfirstlane_b32 s10, v3
	v_sub_u32_e32 v3, 0, v2
	v_rcp_iflag_f32_e32 v4, v4
	v_add_u32_e32 v5, s10, v1
	v_mul_f32_e32 v4, 0x4f7ffffe, v4
	v_cvt_u32_f32_e32 v4, v4
	v_mul_lo_u32 v1, v3, v4
	v_mul_hi_u32 v1, v4, v1
	v_add_u32_e32 v1, v4, v1
	v_mul_hi_u32 v1, v5, v1
	v_mul_lo_u32 v3, v1, v2
	v_sub_u32_e32 v3, v5, v3
	v_add_u32_e32 v4, 1, v1
	v_cmp_ge_u32_e32 vcc, v3, v2
	s_nop 1
	v_cndmask_b32_e32 v1, v1, v4, vcc
	v_sub_u32_e32 v4, v3, v2
	v_cndmask_b32_e32 v3, v3, v4, vcc
	v_add_u32_e32 v4, 1, v1
	v_cmp_ge_u32_e32 vcc, v3, v2
	v_add_u32_e32 v3, 1, v5
	s_nop 0
	v_cndmask_b32_e32 v1, v1, v4, vcc
	v_mul_lo_u32 v4, v2, v1
	v_add_u32_e32 v2, v4, v2
	v_cmp_ne_u32_e32 vcc, v3, v2
	s_and_saveexec_b64 s[10:11], vcc
	s_xor_b64 s[10:11], exec, s[10:11]
	s_cbranch_execz .LBB0_1656
	v_readlane_b32 s12, v253, 9
	v_readlane_b32 s13, v253, 10
	s_waitcnt lgkmcnt(0)
	s_nop 3
	global_load_dword v0, v113, s[12:13] sc1
	s_waitcnt vmcnt(0)
	v_cmp_eq_u32_e32 vcc, v0, v1
	s_and_saveexec_b64 s[12:13], vcc
	s_cbranch_execz .LBB0_1655
	s_mov_b32 s34, 1
	s_mov_b64 s[14:15], 0
	s_branch .LBB0_1646

.LBB0_1648:
	v_readlane_b32 s18, v253, 9
	v_readlane_b32 s19, v253, 10
	s_add_i32 s34, s34, 1
	s_mov_b64 s[30:31], -1
	s_nop 2
	global_load_dword v0, v113, s[18:19] sc1
	s_waitcnt vmcnt(0)
	v_cmp_ne_u32_e32 vcc, v0, v1
	s_orn2_b64 s[18:19], vcc, exec
	s_branch .LBB0_1645

.LBB0_1710:
	s_or_b64 exec, exec, s[12:13]
	v_cvt_f32_u32_e32 v4, v2
	s_waitcnt vmcnt(0)
	v_readfirstlane_b32 s12, v3
	v_sub_u32_e32 v3, 0, v2
	v_rcp_iflag_f32_e32 v4, v4
	v_add_u32_e32 v5, s12, v1
	v_mul_f32_e32 v4, 0x4f7ffffe, v4
	v_cvt_u32_f32_e32 v4, v4
	v_mul_lo_u32 v1, v3, v4
	v_mul_hi_u32 v1, v4, v1
	v_add_u32_e32 v1, v4, v1
	v_mul_hi_u32 v1, v5, v1
	v_mul_lo_u32 v3, v1, v2
	v_sub_u32_e32 v3, v5, v3
	v_add_u32_e32 v4, 1, v1
	v_cmp_ge_u32_e32 vcc, v3, v2
	s_nop 1
	v_cndmask_b32_e32 v1, v1, v4, vcc
	v_sub_u32_e32 v4, v3, v2
	v_cndmask_b32_e32 v3, v3, v4, vcc
	v_add_u32_e32 v4, 1, v1
	v_cmp_ge_u32_e32 vcc, v3, v2
	v_add_u32_e32 v3, 1, v5
	s_nop 0
	v_cndmask_b32_e32 v1, v1, v4, vcc
	v_mul_lo_u32 v4, v2, v1
	v_add_u32_e32 v2, v4, v2
	v_cmp_ne_u32_e32 vcc, v3, v2
	s_and_saveexec_b64 s[12:13], vcc
	s_xor_b64 s[12:13], exec, s[12:13]
	s_cbranch_execz .LBB0_1724
	v_readlane_b32 s14, v253, 9
	v_readlane_b32 s15, v253, 10
	s_waitcnt lgkmcnt(0)
	s_nop 3
	global_load_dword v0, v113, s[14:15] sc1
	s_waitcnt vmcnt(0)
	v_cmp_eq_u32_e32 vcc, v0, v1
	s_and_saveexec_b64 s[14:15], vcc
	s_cbranch_execz .LBB0_1723
	s_mov_b32 s34, 1
	s_mov_b64 s[16:17], 0
	s_branch .LBB0_1714

.LBB0_1716:
	v_readlane_b32 s30, v253, 9
	v_readlane_b32 s31, v253, 10
	s_add_i32 s34, s34, 1
	s_mov_b64 s[36:37], -1
	s_nop 2
	global_load_dword v0, v113, s[30:31] sc1
	s_waitcnt vmcnt(0)
	v_cmp_ne_u32_e32 vcc, v0, v1
	s_orn2_b64 s[30:31], vcc, exec
	s_branch .LBB0_1713
